# all 7 skinny GEMM instances: fragments via row-contiguous LDS-DMA staging (two K halves) + ds_read_b128
# speedup vs baseline: 1.0299x; 1.0028x over previous
; #define LAS __attribute__((address_space(3)))
;     __device__ __forceinline__ void prefetch4(int row, int col, Pre& p) const { p.gw = *(const u32x2*)(Zg + (size_t)row * INC + col); if (SECOND) p.pw = *(const u32x2*)(O + (size_t)row * DM + col); }
; template <int CT, class Epi> __device__ __forceinline__ void skinny_gemm(LAS unsigned char* lds, const bf16_t* A, const bf16_t* Bt, int N, int K, const Epi& E, int first) {
;     ...
;         const bf16_t* ap = A + (size_t)(NTOK_P + mt * 64 + r) * K + wave * kw + 8 * qd;
;         const bf16_t* bp = Bt + (size_t)(nt * 16 * CT + r) * K + wave * kw + 8 * qd;
;         typename Epi::Pre pre[CT / 2];
; #pragma unroll
;         for (int e = 0; e < CT / 2; ++e) { const int idx = tid + e * 512; E.prefetch4(NTOK_P + mt * 64 + idx / (4 * CT), nt * 16 * CT + (idx % (4 * CT)) * 4, pre[e]); }
;         f32x4 acc[4][CT];
; #pragma unroll
;         for (int rt = 0; rt < 4; ++rt)
; #pragma unroll
;             for (int ct = 0; ct < CT; ++ct) acc[rt][ct] = (f32x4){0.f, 0.f, 0.f, 0.f};
;     ...
;         if (nsteps >= 4) {
; #pragma unroll 1
;             for (int s0 = 0; s0 < nsteps; s0 += 4) SKINNY_GROUP(4, s0);
;         } else SKINNY_GROUP(2, 0);
;     ...
; #pragma unroll
;         for (int rt = 0; rt < 4; ++rt)
; #pragma unroll
;             for (int ct = 0; ct < CT; ++ct) *(LAS f32x4*)(red + wave * (64 * 16 * CT) + (rt * 16 + r) * (16 * CT) + ct * 16 + 4 * qd) = acc[rt][ct];
.LBB0_590:
	s_and_b32 s7, s0, 0x1c0
	s_bitset1_b32 s7, 14
	v_or_b32_e32 v0, s7, v22
	v_lshlrev_b32_e32 v0, 10, v0
	s_and_b32 s10, s1, 0xffffffe0
	v_lshl_add_u64 v[36:37], v[2:3], 0, v[0:1]
	v_or_b32_e32 v28, s10, v22
	v_add_co_u32_e32 v44, vcc, s84, v36
	v_ashrrev_i32_e32 v29, 31, v28
	s_nop 0
	v_addc_co_u32_e32 v45, vcc, 0, v37, vcc
	v_lshlrev_b64 v[32:33], 10, v[28:29]
	v_add_u32_e32 v28, s7, v23
	v_add_co_u32_e32 v52, vcc, s85, v36
	s_and_b32 s7, s6, 0x3ffffff8
	v_ashrrev_i32_e32 v29, 31, v28
	v_addc_co_u32_e32 v53, vcc, 0, v37, vcc
	v_add_lshl_u32 v30, s7, v24, 2
	v_lshlrev_b64 v[92:93], 10, v[28:29]
	v_add_co_u32_e32 v60, vcc, s72, v36
	v_lshl_add_u64 v[28:29], s[40:41], 0, v[92:93]
	v_ashrrev_i32_e32 v31, 31, v30
	s_waitcnt vmcnt(2)
	v_lshl_add_u64 v[68:69], v[20:21], 0, v[32:33]
	v_addc_co_u32_e32 v61, vcc, 0, v37, vcc
	v_lshl_add_u64 v[28:29], v[30:31], 1, v[28:29]
	v_add_co_u32_e32 v76, vcc, s84, v68
	global_load_dwordx2 v[94:95], v[28:29], off
	v_lshl_add_u64 v[28:29], v[30:31], 2, s[8:9]
	v_addc_co_u32_e32 v77, vcc, 0, v69, vcc
	global_load_dwordx4 v[28:31], v[28:29], off
	s_nop 0
	s_mov_b32 s100, 0x2000
	s_mov_b32 s101, 0
	v_readfirstlane_b32 s98, v184
	v_and_b32_e32 v246, 63, v184
	s_nop 1
	s_lshr_b32 s98, s98, 6
	s_lshl_b32 s99, s98, 12
	s_add_i32 s99, s99, 0x10000
	s_lshl_b32 s98, s98, 13
	v_and_b32_e32 v247, 15, v246
	v_lshrrev_b32_e32 v248, 4, v246
	v_lshrrev_b32_e32 v249, 3, v246
	v_and_b32_e32 v246, 7, v246
	v_xor_b32_e32 v246, v246, v249
	v_sub_u32_e32 v249, v249, v247
	v_sub_u32_e32 v246, v246, v248
	v_lshlrev_b32_e32 v249, 10, v249
	v_lshl_add_u32 v240, v246, 4, v249
	v_ashrrev_i32_e32 v241, 31, v240
	v_and_b32_e32 v246, 7, v247
	v_xor_b32_e32 v246, v246, v248
	v_lshlrev_b32_e32 v246, 4, v246
	v_lshl_add_u32 v246, v247, 7, v246
	v_add_u32_e32 v242, s98, v246
	v_xor_b32_e32 v243, 64, v242
	v_add_u32_e32 v244, s99, v246
	v_xor_b32_e32 v245, 64, v244
	s_mov_b32 m0, s98
	v_lshl_add_u64 v[236:237], v[36:37], 0, v[240:241]
	global_load_lds_dwordx4 v[236:237], off
	s_add_i32 m0, s98, 0x400
	v_lshl_add_u64 v[236:237], v[236:237], 0, s[100:101]
	global_load_lds_dwordx4 v[236:237], off
	s_add_i32 m0, s98, 0x800
	v_lshl_add_u64 v[236:237], v[236:237], 0, s[100:101]
	global_load_lds_dwordx4 v[236:237], off
	s_add_i32 m0, s98, 0xc00
	v_lshl_add_u64 v[236:237], v[236:237], 0, s[100:101]
	global_load_lds_dwordx4 v[236:237], off
	s_add_i32 m0, s98, 0x1000
	v_lshl_add_u64 v[236:237], v[236:237], 0, s[100:101]
	global_load_lds_dwordx4 v[236:237], off
	s_add_i32 m0, s98, 0x1400
	v_lshl_add_u64 v[236:237], v[236:237], 0, s[100:101]
	global_load_lds_dwordx4 v[236:237], off
	s_add_i32 m0, s98, 0x1800
	v_lshl_add_u64 v[236:237], v[236:237], 0, s[100:101]
	global_load_lds_dwordx4 v[236:237], off
	s_add_i32 m0, s98, 0x1c00
	v_lshl_add_u64 v[236:237], v[236:237], 0, s[100:101]
	global_load_lds_dwordx4 v[236:237], off
	s_mov_b32 m0, s99
	v_lshl_add_u64 v[238:239], v[68:69], 0, v[240:241]
	global_load_lds_dwordx4 v[238:239], off
	s_add_i32 m0, s99, 0x400
	v_lshl_add_u64 v[238:239], v[238:239], 0, s[100:101]
	global_load_lds_dwordx4 v[238:239], off
	s_add_i32 m0, s99, 0x800
	v_lshl_add_u64 v[238:239], v[238:239], 0, s[100:101]
	global_load_lds_dwordx4 v[238:239], off
	s_add_i32 m0, s99, 0xc00
	v_lshl_add_u64 v[238:239], v[238:239], 0, s[100:101]
	global_load_lds_dwordx4 v[238:239], off
	s_waitcnt vmcnt(0)
	ds_read_b128 v[32:35], v242
	ds_read_b128 v[40:43], v242 offset:2048
	ds_read_b128 v[48:51], v242 offset:4096
	ds_read_b128 v[56:59], v242 offset:6144
	ds_read_b128 v[36:39], v243
	ds_read_b128 v[44:47], v243 offset:2048
	ds_read_b128 v[52:55], v243 offset:4096
	ds_read_b128 v[60:63], v243 offset:6144
	ds_read_b128 v[64:67], v244
	ds_read_b128 v[72:75], v244 offset:2048
	ds_read_b128 v[68:71], v245
	ds_read_b128 v[76:79], v245 offset:2048
	s_waitcnt lgkmcnt(0)
	s_nop 0
	s_nop 0
	s_nop 0
	s_nop 0
	s_nop 0
	s_nop 0
	s_nop 0
	s_nop 0
	s_nop 0
	s_nop 0
	s_nop 0
	v_mfma_f32_16x16x32_bf16 v[80:83], v[64:67], v[32:35], 0
	v_mfma_f32_16x16x32_bf16 v[32:35], v[72:75], v[32:35], 0
	v_mfma_f32_16x16x32_bf16 v[84:87], v[64:67], v[40:43], 0
	v_mfma_f32_16x16x32_bf16 v[40:43], v[72:75], v[40:43], 0
	v_mfma_f32_16x16x32_bf16 v[88:91], v[64:67], v[48:51], 0
	v_mfma_f32_16x16x32_bf16 v[48:51], v[72:75], v[48:51], 0
	v_mfma_f32_16x16x32_bf16 v[64:67], v[64:67], v[56:59], 0
	v_mfma_f32_16x16x32_bf16 v[56:59], v[72:75], v[56:59], 0
	v_mfma_f32_16x16x32_bf16 v[72:75], v[68:71], v[36:39], v[80:83]
	v_mfma_f32_16x16x32_bf16 v[32:35], v[76:79], v[36:39], v[32:35]
	v_mfma_f32_16x16x32_bf16 v[36:39], v[68:71], v[44:47], v[84:87]
	v_mfma_f32_16x16x32_bf16 v[40:43], v[76:79], v[44:47], v[40:43]
	v_mfma_f32_16x16x32_bf16 v[44:47], v[68:71], v[52:55], v[88:91]
	v_mfma_f32_16x16x32_bf16 v[48:51], v[76:79], v[52:55], v[48:51]
	v_mfma_f32_16x16x32_bf16 v[52:55], v[68:71], v[60:63], v[64:67]
	v_mfma_f32_16x16x32_bf16 v[56:59], v[76:79], v[60:63], v[56:59]
	ds_write_b128 v27, v[72:75]
	s_nop 0
	ds_write_b128 v27, v[32:35] offset:64
	ds_write_b128 v27, v[36:39] offset:2048
	ds_write_b128 v27, v[40:43] offset:2112
	ds_write_b128 v27, v[44:47] offset:4096
	ds_write_b128 v27, v[48:51] offset:4160
	ds_write_b128 v27, v[52:55] offset:6144
	ds_write_b128 v27, v[56:59] offset:6208
	s_waitcnt lgkmcnt(0)
	s_barrier
; #define LAS __attribute__((address_space(3)))
; __device__ __forceinline__ float bflo(unsigned w) { return __uint_as_float(w << 16); }
; __device__ __forceinline__ float bfhi(unsigned w) { return __uint_as_float(w & 0xffff0000u); }
; __device__ __forceinline__ unsigned pk2(float lo, float hi) { return pg8::cvt_pk_bf16(lo, hi); }
; __device__ __forceinline__ float sigm(float x) { return __builtin_amdgcn_rcpf(1.f + __builtin_amdgcn_exp2f(-LOG2E * x)); }
;     __device__ __forceinline__ void apply4(int row, int col, f32x4 v, const Pre& p) const {
;         const u32x2 yw = p.yw; const f32x4 bb = p.bb;
;         u32x2 w; w.x = pk2(bflo(yw.x) * sigm(v[0] + bb[0]), bfhi(yw.x) * sigm(v[1] + bb[1])); w.y = pk2(bflo(yw.y) * sigm(v[2] + bb[2]), bfhi(yw.y) * sigm(v[3] + bb[3]));
;         *(u32x2*)(O + (size_t)row * 512 + col) = w;
; template <int CT, class Epi> __device__ __forceinline__ void skinny_gemm(LAS unsigned char* lds, const bf16_t* A, const bf16_t* Bt, int N, int K, const Epi& E, int first) {
;     ...
; #pragma unroll
;         for (int e = 0; e < CT / 2; ++e) { const int idx = tid + e * 512, row = idx / (4 * CT), c4 = idx % (4 * CT);
;             f32x4 v = *(const LAS f32x4*)(red + row * (16 * CT) + c4 * 4);
; #pragma unroll
;             for (int w = 1; w < 8; ++w) v = v + *(const LAS f32x4*)(red + w * (64 * 16 * CT) + row * (16 * CT) + c4 * 4);
;             E.apply4(NTOK_P + mt * 64 + row, nt * 16 * CT + c4 * 4, v, pre[e]); }
	ds_read_b128 v[32:35], v26
	ds_read_b128 v[36:39], v26 offset:8192
	ds_read_b128 v[40:43], v26 offset:16384
	ds_read_b128 v[44:47], v26 offset:24576
	v_lshlrev_b32_e32 v0, 16, v94
	v_and_b32_e32 v52, 0xffff0000, v94
	s_waitcnt lgkmcnt(2)
	v_pk_add_f32 v[34:35], v[34:35], v[38:39]
	v_pk_add_f32 v[32:33], v[32:33], v[36:37]
	s_waitcnt lgkmcnt(1)
	v_pk_add_f32 v[34:35], v[34:35], v[42:43]
	v_pk_add_f32 v[36:37], v[32:33], v[40:41]
	s_waitcnt lgkmcnt(0)
	v_pk_add_f32 v[48:49], v[34:35], v[46:47]
	ds_read_b128 v[32:35], v26 offset:32768
	v_pk_add_f32 v[50:51], v[36:37], v[44:45]
	ds_read_b128 v[36:39], v26 offset:40960
	ds_read_b128 v[40:43], v26 offset:49152
	ds_read_b128 v[44:47], v26 offset:57344
	v_lshlrev_b32_e32 v53, 16, v95
	v_and_b32_e32 v54, 0xffff0000, v95
	s_waitcnt lgkmcnt(3)
	v_pk_add_f32 v[32:33], v[50:51], v[32:33]
	v_pk_add_f32 v[34:35], v[48:49], v[34:35]
	s_waitcnt lgkmcnt(2)
	v_pk_add_f32 v[32:33], v[32:33], v[36:37]
	v_pk_add_f32 v[34:35], v[34:35], v[38:39]
	s_waitcnt lgkmcnt(1)
	v_pk_add_f32 v[32:33], v[32:33], v[40:41]
	v_pk_add_f32 v[34:35], v[34:35], v[42:43]
	s_waitcnt lgkmcnt(0)
	v_pk_add_f32 v[32:33], v[32:33], v[44:45]
	v_pk_add_f32 v[34:35], v[34:35], v[46:47]
	v_add_f32_e32 v28, v28, v32
	v_mul_f32_e32 v28, 0xbfb8aa3b, v28
	v_exp_f32_e32 v28, v28
	v_add_f32_e32 v30, v30, v34
	v_mul_f32_e32 v30, 0xbfb8aa3b, v30
	v_add_f32_e32 v31, v31, v35
	v_add_f32_e32 v28, 1.0, v28
	v_rcp_f32_e32 v32, v28
	v_add_f32_e32 v28, v29, v33
	v_mul_f32_e32 v28, 0xbfb8aa3b, v28
	v_exp_f32_e32 v33, v28
	v_exp_f32_e32 v30, v30
	v_mul_f32_e32 v31, 0xbfb8aa3b, v31
	v_exp_f32_e32 v31, v31
	v_mul_f32_e32 v0, v32, v0
	v_add_f32_e32 v32, 1.0, v33
	v_rcp_f32_e32 v32, v32
	v_add_f32_e32 v30, 1.0, v30
	v_rcp_f32_e32 v33, v30
	v_add_f32_e32 v30, 1.0, v31
	v_rcp_f32_e32 v31, v30
	v_add_u32_e32 v28, s10, v25
	v_mul_f32_e32 v30, v32, v52
	v_ashrrev_i32_e32 v29, 31, v28
	v_cvt_pk_bf16_f32 v30, v0, v30
	v_mul_f32_e32 v0, v33, v53
	v_lshl_add_u64 v[32:33], s[50:51], 0, v[92:93]
	s_add_i32 s6, s6, s34
	s_add_i32 s1, s1, s83
	s_add_i32 s0, s0, s82
	v_mul_f32_e32 v31, v31, v54
	v_lshl_add_u64 v[28:29], v[28:29], 1, v[32:33]
	s_cmpk_lt_i32 s6, 0x80
	v_cvt_pk_bf16_f32 v31, v0, v31
	global_store_dwordx2 v[28:29], v[30:31], off
	s_barrier
	s_cbranch_scc1 .LBB0_590

; #define LAS __attribute__((address_space(3)))
; __device__ __forceinline__ float bflo(unsigned w) { return __uint_as_float(w << 16); }
; __device__ __forceinline__ float bfhi(unsigned w) { return __uint_as_float(w & 0xffff0000u); }
;     __device__ __forceinline__ void apply4(int row, int col, f32x4 v, const Pre& p) const {
;         const u32x2 gw = p.gw; bf16_t* op = O + (size_t)row * DM + col;
;         v = (f32x4){bflo(gw.x) * v[0], bfhi(gw.x) * v[1], bflo(gw.y) * v[2], bfhi(gw.y) * v[3]};
;         if (SECOND) { const u32x2 pw = p.pw; v = v + (f32x4){bflo(pw.x), bfhi(pw.x), bflo(pw.y), bfhi(pw.y)}; }
;         u32x2 w; w.x = pk2(v[0], v[1]); w.y = pk2(v[2], v[3]); *(u32x2*)op = w;
; template <int CT, class Epi> __device__ __forceinline__ void skinny_gemm(LAS unsigned char* lds, const bf16_t* A, const bf16_t* Bt, int N, int K, const Epi& E, int first) {
;     ...
;         const bf16_t* ap = A + (size_t)(NTOK_P + mt * 64 + r) * K + wave * kw + 8 * qd;
;         const bf16_t* bp = Bt + (size_t)(nt * 16 * CT + r) * K + wave * kw + 8 * qd;
;         typename Epi::Pre pre[CT / 2];
; #pragma unroll
;         for (int e = 0; e < CT / 2; ++e) { const int idx = tid + e * 512; E.prefetch4(NTOK_P + mt * 64 + idx / (4 * CT), nt * 16 * CT + (idx % (4 * CT)) * 4, pre[e]); }
;         f32x4 acc[4][CT];
; #pragma unroll
;         for (int rt = 0; rt < 4; ++rt)
; #pragma unroll
;             for (int ct = 0; ct < CT; ++ct) acc[rt][ct] = (f32x4){0.f, 0.f, 0.f, 0.f};
;     ...
;         if (nsteps >= 4) {
; #pragma unroll 1
;             for (int s0 = 0; s0 < nsteps; s0 += 4) SKINNY_GROUP(4, s0);
;         } else SKINNY_GROUP(2, 0);
;     ...
; #pragma unroll
;         for (int rt = 0; rt < 4; ++rt)
; #pragma unroll
;             for (int ct = 0; ct < CT; ++ct) *(LAS f32x4*)(red + wave * (64 * 16 * CT) + (rt * 16 + r) * (16 * CT) + ct * 16 + 4 * qd) = acc[rt][ct];
;         __syncthreads();
; #pragma unroll
;         for (int e = 0; e < CT / 2; ++e) { const int idx = tid + e * 512, row = idx / (4 * CT), c4 = idx % (4 * CT);
;             f32x4 v = *(const LAS f32x4*)(red + row * (16 * CT) + c4 * 4);
; #pragma unroll
;             for (int w = 1; w < 8; ++w) v = v + *(const LAS f32x4*)(red + w * (64 * 16 * CT) + row * (16 * CT) + c4 * 4);
;             E.apply4(NTOK_P + mt * 64 + row, nt * 16 * CT + c4 * 4, v, pre[e]); }
.LBB0_685:
	s_and_b32 s5, s0, 0x1c0
	s_bitset1_b32 s5, 14
	v_or_b32_e32 v0, s5, v22
	v_lshlrev_b32_e32 v0, 10, v0
	v_lshl_add_u64 v[36:37], v[2:3], 0, v[0:1]
	s_waitcnt vmcnt(3)
	v_add_co_u32_e32 v64, vcc, s84, v36
	s_and_b32 s8, s1, 0xffffffe0
	s_nop 0
	v_addc_co_u32_e32 v65, vcc, 0, v37, vcc
	v_or_b32_e32 v28, s8, v22
	v_add_co_u32_e32 v52, vcc, s85, v36
	v_ashrrev_i32_e32 v29, 31, v28
	s_nop 0
	v_addc_co_u32_e32 v53, vcc, 0, v37, vcc
	v_lshlrev_b64 v[28:29], 10, v[28:29]
	v_add_u32_e32 v88, s5, v23
	s_and_b32 s5, s4, 0x3ffffff8
	v_add_co_u32_e32 v60, vcc, s72, v36
	v_add_lshl_u32 v30, s5, v24, 2
	v_mov_b64_e32 v[32:33], s[10:11]
	s_waitcnt vmcnt(2)
	v_lshl_add_u64 v[68:69], v[20:21], 0, v[28:29]
	v_addc_co_u32_e32 v61, vcc, 0, v37, vcc
	v_mad_i64_i32 v[32:33], s[6:7], v88, s87, v[32:33]
	v_ashrrev_i32_e32 v31, 31, v30
	s_waitcnt vmcnt(1)
	v_add_co_u32_e32 v72, vcc, s84, v68
	v_lshl_add_u64 v[30:31], v[30:31], 1, v[32:33]
	s_nop 0
	v_addc_co_u32_e32 v73, vcc, 0, v69, vcc
	global_load_dwordx2 v[90:91], v[30:31], off
	s_nop 0
	s_mov_b32 s100, 0x2000
	s_mov_b32 s101, 0
	v_readfirstlane_b32 s98, v184
	v_and_b32_e32 v246, 63, v184
	s_nop 1
	s_lshr_b32 s98, s98, 6
	s_lshl_b32 s99, s98, 12
	s_add_i32 s99, s99, 0x10000
	s_lshl_b32 s98, s98, 13
	v_and_b32_e32 v247, 15, v246
	v_lshrrev_b32_e32 v248, 4, v246
	v_lshrrev_b32_e32 v249, 3, v246
	v_and_b32_e32 v246, 7, v246
	v_xor_b32_e32 v246, v246, v249
	v_sub_u32_e32 v249, v249, v247
	v_sub_u32_e32 v246, v246, v248
	v_lshlrev_b32_e32 v249, 10, v249
	v_lshl_add_u32 v240, v246, 4, v249
	v_ashrrev_i32_e32 v241, 31, v240
	v_and_b32_e32 v246, 7, v247
	v_xor_b32_e32 v246, v246, v248
	v_lshlrev_b32_e32 v246, 4, v246
	v_lshl_add_u32 v246, v247, 7, v246
	v_add_u32_e32 v242, s98, v246
	v_xor_b32_e32 v243, 64, v242
	v_add_u32_e32 v244, s99, v246
	v_xor_b32_e32 v245, 64, v244
	s_mov_b32 m0, s98
	v_lshl_add_u64 v[236:237], v[36:37], 0, v[240:241]
	global_load_lds_dwordx4 v[236:237], off
	s_add_i32 m0, s98, 0x400
	v_lshl_add_u64 v[236:237], v[236:237], 0, s[100:101]
	global_load_lds_dwordx4 v[236:237], off
	s_add_i32 m0, s98, 0x800
	v_lshl_add_u64 v[236:237], v[236:237], 0, s[100:101]
	global_load_lds_dwordx4 v[236:237], off
	s_add_i32 m0, s98, 0xc00
	v_lshl_add_u64 v[236:237], v[236:237], 0, s[100:101]
	global_load_lds_dwordx4 v[236:237], off
	s_add_i32 m0, s98, 0x1000
	v_lshl_add_u64 v[236:237], v[236:237], 0, s[100:101]
	global_load_lds_dwordx4 v[236:237], off
	s_add_i32 m0, s98, 0x1400
	v_lshl_add_u64 v[236:237], v[236:237], 0, s[100:101]
	global_load_lds_dwordx4 v[236:237], off
	s_add_i32 m0, s98, 0x1800
	v_lshl_add_u64 v[236:237], v[236:237], 0, s[100:101]
	global_load_lds_dwordx4 v[236:237], off
	s_add_i32 m0, s98, 0x1c00
	v_lshl_add_u64 v[236:237], v[236:237], 0, s[100:101]
	global_load_lds_dwordx4 v[236:237], off
	s_mov_b32 m0, s99
	v_lshl_add_u64 v[238:239], v[68:69], 0, v[240:241]
	global_load_lds_dwordx4 v[238:239], off
	s_add_i32 m0, s99, 0x400
	v_lshl_add_u64 v[238:239], v[238:239], 0, s[100:101]
	global_load_lds_dwordx4 v[238:239], off
	s_add_i32 m0, s99, 0x800
	v_lshl_add_u64 v[238:239], v[238:239], 0, s[100:101]
	global_load_lds_dwordx4 v[238:239], off
	s_add_i32 m0, s99, 0xc00
	v_lshl_add_u64 v[238:239], v[238:239], 0, s[100:101]
	global_load_lds_dwordx4 v[238:239], off
	s_waitcnt vmcnt(0)
	ds_read_b128 v[28:31], v242
	ds_read_b128 v[64:67], v242 offset:2048
	ds_read_b128 v[40:43], v242 offset:4096
	ds_read_b128 v[48:51], v242 offset:6144
	ds_read_b128 v[36:39], v243
	ds_read_b128 v[44:47], v243 offset:2048
	ds_read_b128 v[52:55], v243 offset:4096
	ds_read_b128 v[60:63], v243 offset:6144
	ds_read_b128 v[32:35], v244
	ds_read_b128 v[56:59], v244 offset:2048
	ds_read_b128 v[68:71], v245
	ds_read_b128 v[72:75], v245 offset:2048
	s_waitcnt lgkmcnt(0)
	s_nop 0
	s_nop 0
	s_nop 0
	s_nop 0
	s_nop 0
	s_nop 0
	s_nop 0
	s_nop 0
	v_ashrrev_i32_e32 v89, 31, v88
	v_mfma_f32_16x16x32_bf16 v[76:79], v[32:35], v[28:31], 0
	v_mfma_f32_16x16x32_bf16 v[28:31], v[56:59], v[28:31], 0
	v_mfma_f32_16x16x32_bf16 v[80:83], v[32:35], v[64:67], 0
	v_mfma_f32_16x16x32_bf16 v[64:67], v[56:59], v[64:67], 0
	v_mfma_f32_16x16x32_bf16 v[84:87], v[32:35], v[40:43], 0
	v_mfma_f32_16x16x32_bf16 v[40:43], v[56:59], v[40:43], 0
	v_mfma_f32_16x16x32_bf16 v[32:35], v[32:35], v[48:51], 0
	v_mfma_f32_16x16x32_bf16 v[48:51], v[56:59], v[48:51], 0
	v_mfma_f32_16x16x32_bf16 v[56:59], v[68:71], v[36:39], v[76:79]
	v_mfma_f32_16x16x32_bf16 v[28:31], v[72:75], v[36:39], v[28:31]
	v_mfma_f32_16x16x32_bf16 v[36:39], v[68:71], v[44:47], v[80:83]
	v_mfma_f32_16x16x32_bf16 v[44:47], v[72:75], v[44:47], v[64:67]
	v_mfma_f32_16x16x32_bf16 v[64:67], v[68:71], v[52:55], v[84:87]
	v_mfma_f32_16x16x32_bf16 v[40:43], v[72:75], v[52:55], v[40:43]
	v_mfma_f32_16x16x32_bf16 v[32:35], v[68:71], v[60:63], v[32:35]
	v_mfma_f32_16x16x32_bf16 v[48:51], v[72:75], v[60:63], v[48:51]
	ds_write_b128 v27, v[56:59]
	s_nop 0
	ds_write_b128 v27, v[28:31] offset:64
	ds_write_b128 v27, v[36:39] offset:2048
	ds_write_b128 v27, v[44:47] offset:2112
	ds_write_b128 v27, v[64:67] offset:4096
	ds_write_b128 v27, v[40:43] offset:4160
	ds_write_b128 v27, v[32:35] offset:6144
	ds_write_b128 v27, v[48:51] offset:6208
	s_waitcnt lgkmcnt(0)
	s_barrier
	ds_read_b128 v[28:31], v26
	ds_read_b128 v[32:35], v26 offset:8192
	ds_read_b128 v[36:39], v26 offset:16384
	ds_read_b128 v[40:43], v26 offset:24576
	v_add_u32_e32 v44, s8, v25
	v_lshlrev_b64 v[46:47], 11, v[88:89]
	s_waitcnt lgkmcnt(2)
	v_pk_add_f32 v[30:31], v[30:31], v[34:35]
	v_pk_add_f32 v[32:33], v[28:29], v[32:33]
	s_waitcnt lgkmcnt(1)
	v_pk_add_f32 v[34:35], v[30:31], v[38:39]
	ds_read_b128 v[28:31], v26 offset:32768
	v_pk_add_f32 v[32:33], v[32:33], v[36:37]
	s_waitcnt lgkmcnt(1)
	v_pk_add_f32 v[36:37], v[34:35], v[42:43]
	v_pk_add_f32 v[40:41], v[32:33], v[40:41]
	ds_read_b128 v[32:35], v26 offset:40960
	s_waitcnt lgkmcnt(1)
	v_pk_add_f32 v[42:43], v[36:37], v[30:31]
	ds_read_b128 v[36:39], v26 offset:49152
	v_pk_add_f32 v[40:41], v[40:41], v[28:29]
	ds_read_b128 v[28:31], v26 offset:57344
	s_waitcnt lgkmcnt(2)
	v_pk_add_f32 v[34:35], v[42:43], v[34:35]
	v_pk_add_f32 v[32:33], v[40:41], v[32:33]
	s_waitcnt lgkmcnt(1)
	v_pk_add_f32 v[34:35], v[34:35], v[38:39]
	v_pk_add_f32 v[32:33], v[32:33], v[36:37]
	v_ashrrev_i32_e32 v45, 31, v44
	v_lshlrev_b32_e32 v0, 16, v90
	v_and_b32_e32 v48, 0xffff0000, v90
	v_lshlrev_b32_e32 v49, 16, v91
	s_waitcnt lgkmcnt(0)
	v_pk_add_f32 v[30:31], v[34:35], v[30:31]
	v_pk_add_f32 v[28:29], v[32:33], v[28:29]
	v_lshl_add_u64 v[32:33], s[68:69], 0, v[46:47]
	s_add_i32 s4, s4, s34
	s_add_i32 s1, s1, s83
	s_add_i32 s0, s0, s82
	v_and_b32_e32 v50, 0xffff0000, v91
	v_lshl_add_u64 v[32:33], v[44:45], 1, v[32:33]
	v_mul_f32_e32 v0, v28, v0
	v_mul_f32_e32 v28, v29, v48
	v_mul_f32_e32 v29, v30, v49
	s_cmpk_lt_i32 s4, 0x100
	v_mul_f32_e32 v30, v31, v50
	v_cvt_pk_bf16_f32 v28, v0, v28
	v_cvt_pk_bf16_f32 v29, v29, v30
	global_store_dwordx2 v[32:33], v[28:29], off
	s_barrier
	s_cbranch_scc1 .LBB0_685

; #define LAS __attribute__((address_space(3)))
;     __device__ __forceinline__ void prefetch4(int row, int col, Pre& p) const { p.gw = *(const u32x2*)(Zg + (size_t)row * INC + col); if (SECOND) p.pw = *(const u32x2*)(O + (size_t)row * DM + col); }
; template <int CT, class Epi> __device__ __forceinline__ void skinny_gemm(LAS unsigned char* lds, const bf16_t* A, const bf16_t* Bt, int N, int K, const Epi& E, int first) {
;     ...
;         const bf16_t* ap = A + (size_t)(NTOK_P + mt * 64 + r) * K + wave * kw + 8 * qd;
;         const bf16_t* bp = Bt + (size_t)(nt * 16 * CT + r) * K + wave * kw + 8 * qd;
;         typename Epi::Pre pre[CT / 2];
; #pragma unroll
;         for (int e = 0; e < CT / 2; ++e) { const int idx = tid + e * 512; E.prefetch4(NTOK_P + mt * 64 + idx / (4 * CT), nt * 16 * CT + (idx % (4 * CT)) * 4, pre[e]); }
;         f32x4 acc[4][CT];
; #pragma unroll
;         for (int rt = 0; rt < 4; ++rt)
; #pragma unroll
;             for (int ct = 0; ct < CT; ++ct) acc[rt][ct] = (f32x4){0.f, 0.f, 0.f, 0.f};
;     ...
;         if (nsteps >= 4) {
; #pragma unroll 1
;             for (int s0 = 0; s0 < nsteps; s0 += 4) SKINNY_GROUP(4, s0);
;         } else SKINNY_GROUP(2, 0);
;     ...
; #pragma unroll
;         for (int rt = 0; rt < 4; ++rt)
; #pragma unroll
;             for (int ct = 0; ct < CT; ++ct) *(LAS f32x4*)(red + wave * (64 * 16 * CT) + (rt * 16 + r) * (16 * CT) + ct * 16 + 4 * qd) = acc[rt][ct];
.LBB0_708:
	s_and_b32 s5, s0, 0x1c0
	s_bitset1_b32 s5, 14
	v_or_b32_e32 v0, s5, v22
	v_add_u32_e32 v30, s5, v23
	s_and_b32 s5, s4, 0x3ffffff8
	v_add_lshl_u32 v32, s5, v24, 2
	v_ashrrev_i32_e32 v31, 31, v30
	v_mov_b64_e32 v[34:35], s[10:11]
	v_mad_i64_i32 v[34:35], s[6:7], v30, s87, v[34:35]
	v_ashrrev_i32_e32 v33, 31, v32
	v_lshlrev_b64 v[30:31], 11, v[30:31]
	v_lshlrev_b64 v[32:33], 1, v[32:33]
	s_waitcnt vmcnt(0)
	v_lshl_add_u64 v[90:91], s[68:69], 0, v[30:31]
	v_lshlrev_b32_e32 v0, 10, v0
	v_lshl_add_u64 v[34:35], v[34:35], 0, v[32:33]
	v_lshl_add_u64 v[30:31], v[90:91], 0, v[32:33]
	v_lshl_add_u64 v[32:33], v[2:3], 0, v[0:1]
	v_add_co_u32_e32 v40, vcc, s84, v32
	s_and_b32 s8, s1, 0xffffffe0
	s_nop 0
	v_addc_co_u32_e32 v41, vcc, 0, v33, vcc
	v_or_b32_e32 v28, s8, v22
	v_add_co_u32_e32 v48, vcc, s85, v32
	v_ashrrev_i32_e32 v29, 31, v28
	s_nop 0
	v_addc_co_u32_e32 v49, vcc, 0, v33, vcc
	v_lshlrev_b64 v[28:29], 10, v[28:29]
	v_add_co_u32_e32 v56, vcc, s72, v32
	v_lshl_add_u64 v[64:65], v[20:21], 0, v[28:29]
	s_nop 0
	v_addc_co_u32_e32 v57, vcc, 0, v33, vcc
	v_add_co_u32_e32 v72, vcc, s84, v64
	global_load_dwordx2 v[88:89], v[34:35], off
	s_nop 0
	v_addc_co_u32_e32 v73, vcc, 0, v65, vcc
	global_load_dwordx2 v[92:93], v[30:31], off
	s_nop 0
	s_mov_b32 s100, 0x2000
	s_mov_b32 s101, 0
	v_readfirstlane_b32 s98, v184
	v_and_b32_e32 v246, 63, v184
	s_nop 1
	s_lshr_b32 s98, s98, 6
	s_lshl_b32 s99, s98, 12
	s_add_i32 s99, s99, 0x10000
	s_lshl_b32 s98, s98, 13
	v_and_b32_e32 v247, 15, v246
	v_lshrrev_b32_e32 v248, 4, v246
	v_lshrrev_b32_e32 v249, 3, v246
	v_and_b32_e32 v246, 7, v246
	v_xor_b32_e32 v246, v246, v249
	v_sub_u32_e32 v249, v249, v247
	v_sub_u32_e32 v246, v246, v248
	v_lshlrev_b32_e32 v249, 10, v249
	v_lshl_add_u32 v240, v246, 4, v249
	v_ashrrev_i32_e32 v241, 31, v240
	v_and_b32_e32 v246, 7, v247
	v_xor_b32_e32 v246, v246, v248
	v_lshlrev_b32_e32 v246, 4, v246
	v_lshl_add_u32 v246, v247, 7, v246
	v_add_u32_e32 v242, s98, v246
	v_xor_b32_e32 v243, 64, v242
	v_add_u32_e32 v244, s99, v246
	v_xor_b32_e32 v245, 64, v244
	s_mov_b32 m0, s98
	v_lshl_add_u64 v[236:237], v[32:33], 0, v[240:241]
	global_load_lds_dwordx4 v[236:237], off
	s_add_i32 m0, s98, 0x400
	v_lshl_add_u64 v[236:237], v[236:237], 0, s[100:101]
	global_load_lds_dwordx4 v[236:237], off
	s_add_i32 m0, s98, 0x800
	v_lshl_add_u64 v[236:237], v[236:237], 0, s[100:101]
	global_load_lds_dwordx4 v[236:237], off
	s_add_i32 m0, s98, 0xc00
	v_lshl_add_u64 v[236:237], v[236:237], 0, s[100:101]
	global_load_lds_dwordx4 v[236:237], off
	s_add_i32 m0, s98, 0x1000
	v_lshl_add_u64 v[236:237], v[236:237], 0, s[100:101]
	global_load_lds_dwordx4 v[236:237], off
	s_add_i32 m0, s98, 0x1400
	v_lshl_add_u64 v[236:237], v[236:237], 0, s[100:101]
	global_load_lds_dwordx4 v[236:237], off
	s_add_i32 m0, s98, 0x1800
	v_lshl_add_u64 v[236:237], v[236:237], 0, s[100:101]
	global_load_lds_dwordx4 v[236:237], off
	s_add_i32 m0, s98, 0x1c00
	v_lshl_add_u64 v[236:237], v[236:237], 0, s[100:101]
	global_load_lds_dwordx4 v[236:237], off
	s_mov_b32 m0, s99
	v_lshl_add_u64 v[238:239], v[64:65], 0, v[240:241]
	global_load_lds_dwordx4 v[238:239], off
	s_add_i32 m0, s99, 0x400
	v_lshl_add_u64 v[238:239], v[238:239], 0, s[100:101]
	global_load_lds_dwordx4 v[238:239], off
	s_add_i32 m0, s99, 0x800
	v_lshl_add_u64 v[238:239], v[238:239], 0, s[100:101]
	global_load_lds_dwordx4 v[238:239], off
	s_add_i32 m0, s99, 0xc00
	v_lshl_add_u64 v[238:239], v[238:239], 0, s[100:101]
	global_load_lds_dwordx4 v[238:239], off
	s_waitcnt vmcnt(0)
	ds_read_b128 v[28:31], v242
	ds_read_b128 v[36:39], v242 offset:2048
	ds_read_b128 v[44:47], v242 offset:4096
	ds_read_b128 v[52:55], v242 offset:6144
	ds_read_b128 v[32:35], v243
	ds_read_b128 v[40:43], v243 offset:2048
	ds_read_b128 v[48:51], v243 offset:4096
	ds_read_b128 v[56:59], v243 offset:6144
	ds_read_b128 v[60:63], v244
	ds_read_b128 v[68:71], v244 offset:2048
	ds_read_b128 v[64:67], v245
	ds_read_b128 v[72:75], v245 offset:2048
	s_waitcnt lgkmcnt(0)
	s_nop 0
	s_nop 0
	s_nop 0
	s_nop 0
	s_nop 0
	s_nop 0
	s_nop 0
	s_nop 0
	s_nop 0
	s_nop 0
	s_nop 0
	v_mfma_f32_16x16x32_bf16 v[76:79], v[60:63], v[28:31], 0
	v_mfma_f32_16x16x32_bf16 v[28:31], v[68:71], v[28:31], 0
	v_mfma_f32_16x16x32_bf16 v[80:83], v[60:63], v[36:39], 0
	v_mfma_f32_16x16x32_bf16 v[36:39], v[68:71], v[36:39], 0
	v_mfma_f32_16x16x32_bf16 v[84:87], v[60:63], v[44:47], 0
	v_mfma_f32_16x16x32_bf16 v[44:47], v[68:71], v[44:47], 0
	v_mfma_f32_16x16x32_bf16 v[60:63], v[60:63], v[52:55], 0
	v_mfma_f32_16x16x32_bf16 v[52:55], v[68:71], v[52:55], 0
	v_mfma_f32_16x16x32_bf16 v[68:71], v[64:67], v[32:35], v[76:79]
	v_mfma_f32_16x16x32_bf16 v[28:31], v[72:75], v[32:35], v[28:31]
	v_mfma_f32_16x16x32_bf16 v[32:35], v[64:67], v[40:43], v[80:83]
	v_mfma_f32_16x16x32_bf16 v[36:39], v[72:75], v[40:43], v[36:39]
	v_mfma_f32_16x16x32_bf16 v[40:43], v[64:67], v[48:51], v[84:87]
	v_mfma_f32_16x16x32_bf16 v[44:47], v[72:75], v[48:51], v[44:47]
	v_mfma_f32_16x16x32_bf16 v[48:51], v[64:67], v[56:59], v[60:63]
	v_mfma_f32_16x16x32_bf16 v[52:55], v[72:75], v[56:59], v[52:55]
	ds_write_b128 v27, v[68:71]
	s_nop 0
	ds_write_b128 v27, v[28:31] offset:64
	ds_write_b128 v27, v[32:35] offset:2048
	ds_write_b128 v27, v[36:39] offset:2112
	ds_write_b128 v27, v[40:43] offset:4096
	ds_write_b128 v27, v[44:47] offset:4160
	ds_write_b128 v27, v[48:51] offset:6144
	ds_write_b128 v27, v[52:55] offset:6208
	s_waitcnt lgkmcnt(0)
	s_barrier
; #define LAS __attribute__((address_space(3)))
; __device__ __forceinline__ float bflo(unsigned w) { return __uint_as_float(w << 16); }
; __device__ __forceinline__ float bfhi(unsigned w) { return __uint_as_float(w & 0xffff0000u); }
; __device__ __forceinline__ unsigned pk2(float lo, float hi) { return pg8::cvt_pk_bf16(lo, hi); }
;     __device__ __forceinline__ void apply4(int row, int col, f32x4 v, const Pre& p) const {
;         const u32x2 gw = p.gw; bf16_t* op = O + (size_t)row * DM + col;
;         v = (f32x4){bflo(gw.x) * v[0], bfhi(gw.x) * v[1], bflo(gw.y) * v[2], bfhi(gw.y) * v[3]};
;         if (SECOND) { const u32x2 pw = p.pw; v = v + (f32x4){bflo(pw.x), bfhi(pw.x), bflo(pw.y), bfhi(pw.y)}; }
;         u32x2 w; w.x = pk2(v[0], v[1]); w.y = pk2(v[2], v[3]); *(u32x2*)op = w;
; template <int CT, class Epi> __device__ __forceinline__ void skinny_gemm(LAS unsigned char* lds, const bf16_t* A, const bf16_t* Bt, int N, int K, const Epi& E, int first) {
;     ...
; #pragma unroll
;         for (int e = 0; e < CT / 2; ++e) { const int idx = tid + e * 512, row = idx / (4 * CT), c4 = idx % (4 * CT);
;             f32x4 v = *(const LAS f32x4*)(red + row * (16 * CT) + c4 * 4);
; #pragma unroll
;             for (int w = 1; w < 8; ++w) v = v + *(const LAS f32x4*)(red + w * (64 * 16 * CT) + row * (16 * CT) + c4 * 4);
;             E.apply4(NTOK_P + mt * 64 + row, nt * 16 * CT + c4 * 4, v, pre[e]); }
	ds_read_b128 v[28:31], v26
	ds_read_b128 v[32:35], v26 offset:8192
	ds_read_b128 v[36:39], v26 offset:16384
	ds_read_b128 v[40:43], v26 offset:24576
	v_add_u32_e32 v44, s8, v25
	v_ashrrev_i32_e32 v45, 31, v44
	s_waitcnt lgkmcnt(2)
	v_pk_add_f32 v[30:31], v[30:31], v[34:35]
	v_pk_add_f32 v[32:33], v[28:29], v[32:33]
	s_waitcnt lgkmcnt(1)
	v_pk_add_f32 v[34:35], v[30:31], v[38:39]
	ds_read_b128 v[28:31], v26 offset:32768
	v_pk_add_f32 v[32:33], v[32:33], v[36:37]
	s_waitcnt lgkmcnt(1)
	v_pk_add_f32 v[36:37], v[34:35], v[42:43]
	v_pk_add_f32 v[40:41], v[32:33], v[40:41]
	ds_read_b128 v[32:35], v26 offset:40960
	s_waitcnt lgkmcnt(1)
	v_pk_add_f32 v[42:43], v[36:37], v[30:31]
	ds_read_b128 v[36:39], v26 offset:49152
	v_pk_add_f32 v[40:41], v[40:41], v[28:29]
	ds_read_b128 v[28:31], v26 offset:57344
	s_waitcnt lgkmcnt(2)
	v_pk_add_f32 v[34:35], v[42:43], v[34:35]
	v_pk_add_f32 v[32:33], v[40:41], v[32:33]
	s_waitcnt lgkmcnt(1)
	v_pk_add_f32 v[34:35], v[34:35], v[38:39]
	v_pk_add_f32 v[32:33], v[32:33], v[36:37]
	v_lshlrev_b32_e32 v46, 16, v92
	v_and_b32_e32 v47, 0xffff0000, v92
	s_waitcnt lgkmcnt(0)
	v_pk_add_f32 v[30:31], v[34:35], v[30:31]
	v_pk_add_f32 v[28:29], v[32:33], v[28:29]
	v_lshlrev_b32_e32 v34, 16, v88
	v_and_b32_e32 v35, 0xffff0000, v88
	s_add_i32 s4, s4, s34
	s_add_i32 s1, s1, s83
	s_add_i32 s0, s0, s82
	v_lshlrev_b32_e32 v48, 16, v93
	v_and_b32_e32 v49, 0xffff0000, v93
	v_lshl_add_u64 v[32:33], v[44:45], 1, v[90:91]
	v_lshlrev_b32_e32 v36, 16, v89
	v_and_b32_e32 v37, 0xffff0000, v89
	v_pk_fma_f32 v[28:29], v[28:29], v[34:35], v[46:47]
	s_cmpk_lt_i32 s4, 0x100
	v_pk_fma_f32 v[30:31], v[30:31], v[36:37], v[48:49]
	v_cvt_pk_bf16_f32 v28, v28, v29
	s_nop 0
	v_cvt_pk_bf16_f32 v29, v30, v31
	global_store_dwordx2 v[32:33], v[28:29], off
	s_barrier
	s_cbranch_scc1 .LBB0_708
